# adds: conv_run prologue loads batched (31 tap loads + 30 boundary-row loads issued together, one wait); sgu_unit weight-staging and GU read-modify-write loads batched with counted vmcnt
# speedup vs baseline: 1.0229x; 1.0058x over previous
; #define LAS __attribute__((address_space(3)))
; __device__ __forceinline__ unsigned cvt_pk_bf16(float lo, float hi) { const f32x2 v = {lo, hi}; const bf16x2_t b = __builtin_convertvector(v, bf16x2_t); return __builtin_bit_cast(unsigned, b); }
; __device__ __forceinline__ void conv_run(LAS unsigned char* lds, const bf16_t* AG, bf16_t* CA, const float* cw, const float* cb, const float* lng, const float* lnb, int unit0, int nun, const int wave_s) {
;     ...
;     const f32x2 bias = *(const f32x2*)(cb + c);
;     const f32x2 g = *(const f32x2*)(lng + c), bb = *(const f32x2*)(lnb + c);
;     LAS unsigned* wl = (LAS unsigned*)(lds + 65536 + 256);
; #pragma unroll
;     for (int j = 0; j < 31; ++j) { const f32x2 w = *(const f32x2*)(cw + j * DM + c); wl[j * 512 + tid] = cvt_pk_bf16(w.x, w.y); }
.LBB0_741:
.LBB0_742:
	v_mov_b32_e32 v0, v1
	v_readlane_b32 s12, v253, 14
	v_mbcnt_lo_u32_b32 v0, -1, v0
	v_mbcnt_hi_u32_b32 v10, -1, v0
	v_add_u32_e32 v0, s12, v10
	v_lshlrev_b32_e32 v8, 1, v0
	v_ashrrev_i32_e32 v9, 31, v8
	v_lshl_add_u64 v[2:3], v[8:9], 2, s[52:53]
	v_lshl_add_u32 v0, v0, 2, 0
	v_add_u32_e32 v132, 0x10100, v0
	v_lshlrev_b32_e32 v11, 2, v8
	s_mov_b64 s[12:13], s[52:53]
	global_load_dwordx2 v[150:151], v11, s[12:13]
	s_add_u32 s12, s12, 0x1000
	s_addc_u32 s13, s13, 0
	global_load_dwordx2 v[152:153], v11, s[12:13]
	s_add_u32 s12, s12, 0x1000
	s_addc_u32 s13, s13, 0
	global_load_dwordx2 v[154:155], v11, s[12:13]
	s_add_u32 s12, s12, 0x1000
	s_addc_u32 s13, s13, 0
	global_load_dwordx2 v[156:157], v11, s[12:13]
	s_add_u32 s12, s12, 0x1000
	s_addc_u32 s13, s13, 0
	global_load_dwordx2 v[158:159], v11, s[12:13]
	s_add_u32 s12, s12, 0x1000
	s_addc_u32 s13, s13, 0
	global_load_dwordx2 v[160:161], v11, s[12:13]
	s_add_u32 s12, s12, 0x1000
	s_addc_u32 s13, s13, 0
	global_load_dwordx2 v[162:163], v11, s[12:13]
	s_add_u32 s12, s12, 0x1000
	s_addc_u32 s13, s13, 0
	global_load_dwordx2 v[164:165], v11, s[12:13]
	s_add_u32 s12, s12, 0x1000
	s_addc_u32 s13, s13, 0
	global_load_dwordx2 v[166:167], v11, s[12:13]
	s_add_u32 s12, s12, 0x1000
	s_addc_u32 s13, s13, 0
	global_load_dwordx2 v[168:169], v11, s[12:13]
	s_add_u32 s12, s12, 0x1000
	s_addc_u32 s13, s13, 0
	global_load_dwordx2 v[170:171], v11, s[12:13]
	s_add_u32 s12, s12, 0x1000
	s_addc_u32 s13, s13, 0
	global_load_dwordx2 v[172:173], v11, s[12:13]
	s_add_u32 s12, s12, 0x1000
	s_addc_u32 s13, s13, 0
	global_load_dwordx2 v[174:175], v11, s[12:13]
	s_add_u32 s12, s12, 0x1000
	s_addc_u32 s13, s13, 0
	global_load_dwordx2 v[176:177], v11, s[12:13]
	s_add_u32 s12, s12, 0x1000
	s_addc_u32 s13, s13, 0
	global_load_dwordx2 v[178:179], v11, s[12:13]
	s_add_u32 s12, s12, 0x1000
	s_addc_u32 s13, s13, 0
	global_load_dwordx2 v[180:181], v11, s[12:13]
	s_add_u32 s12, s12, 0x1000
	s_addc_u32 s13, s13, 0
	global_load_dwordx2 v[182:183], v11, s[12:13]
	s_add_u32 s12, s12, 0x1000
	s_addc_u32 s13, s13, 0
	global_load_dwordx2 v[184:185], v11, s[12:13]
	s_add_u32 s12, s12, 0x1000
	s_addc_u32 s13, s13, 0
	global_load_dwordx2 v[186:187], v11, s[12:13]
	s_add_u32 s12, s12, 0x1000
	s_addc_u32 s13, s13, 0
	global_load_dwordx2 v[188:189], v11, s[12:13]
	s_add_u32 s12, s12, 0x1000
	s_addc_u32 s13, s13, 0
	global_load_dwordx2 v[190:191], v11, s[12:13]
	s_add_u32 s12, s12, 0x1000
	s_addc_u32 s13, s13, 0
	global_load_dwordx2 v[196:197], v11, s[12:13]
	s_add_u32 s12, s12, 0x1000
	s_addc_u32 s13, s13, 0
	global_load_dwordx2 v[198:199], v11, s[12:13]
	s_add_u32 s12, s12, 0x1000
	s_addc_u32 s13, s13, 0
	global_load_dwordx2 v[200:201], v11, s[12:13]
	s_add_u32 s12, s12, 0x1000
	s_addc_u32 s13, s13, 0
	global_load_dwordx2 v[202:203], v11, s[12:13]
	s_add_u32 s12, s12, 0x1000
	s_addc_u32 s13, s13, 0
	global_load_dwordx2 v[204:205], v11, s[12:13]
	s_add_u32 s12, s12, 0x1000
	s_addc_u32 s13, s13, 0
	global_load_dwordx2 v[206:207], v11, s[12:13]
	s_add_u32 s12, s12, 0x1000
	s_addc_u32 s13, s13, 0
	global_load_dwordx2 v[208:209], v11, s[12:13]
	s_add_u32 s12, s12, 0x1000
	s_addc_u32 s13, s13, 0
	global_load_dwordx2 v[210:211], v11, s[12:13]
	s_add_u32 s12, s12, 0x1000
	s_addc_u32 s13, s13, 0
	global_load_dwordx2 v[212:213], v11, s[12:13]
	s_add_u32 s12, s12, 0x1000
	s_addc_u32 s13, s13, 0
	global_load_dwordx2 v[214:215], v11, s[12:13]
	s_waitcnt vmcnt(0)
	v_cvt_pk_bf16_f32 v150, v150, v151
	v_cvt_pk_bf16_f32 v152, v152, v153
	v_cvt_pk_bf16_f32 v154, v154, v155
	v_cvt_pk_bf16_f32 v156, v156, v157
	v_cvt_pk_bf16_f32 v158, v158, v159
	v_cvt_pk_bf16_f32 v160, v160, v161
	v_cvt_pk_bf16_f32 v162, v162, v163
	v_cvt_pk_bf16_f32 v164, v164, v165
	v_cvt_pk_bf16_f32 v166, v166, v167
	v_cvt_pk_bf16_f32 v168, v168, v169
	v_cvt_pk_bf16_f32 v170, v170, v171
	v_cvt_pk_bf16_f32 v172, v172, v173
	v_cvt_pk_bf16_f32 v174, v174, v175
	v_cvt_pk_bf16_f32 v176, v176, v177
	v_cvt_pk_bf16_f32 v178, v178, v179
	v_cvt_pk_bf16_f32 v180, v180, v181
	v_cvt_pk_bf16_f32 v182, v182, v183
	v_cvt_pk_bf16_f32 v184, v184, v185
	v_cvt_pk_bf16_f32 v186, v186, v187
	v_cvt_pk_bf16_f32 v188, v188, v189
	v_cvt_pk_bf16_f32 v190, v190, v191
	v_cvt_pk_bf16_f32 v196, v196, v197
	v_cvt_pk_bf16_f32 v198, v198, v199
	v_cvt_pk_bf16_f32 v200, v200, v201
	v_cvt_pk_bf16_f32 v202, v202, v203
	v_cvt_pk_bf16_f32 v204, v204, v205
	v_cvt_pk_bf16_f32 v206, v206, v207
	v_cvt_pk_bf16_f32 v208, v208, v209
	v_cvt_pk_bf16_f32 v210, v210, v211
	v_cvt_pk_bf16_f32 v212, v212, v213
	v_cvt_pk_bf16_f32 v214, v214, v215
	ds_write2st64_b32 v132, v150, v152 offset0:0 offset1:8
	ds_write2st64_b32 v132, v154, v156 offset0:16 offset1:24
	ds_write2st64_b32 v132, v158, v160 offset0:32 offset1:40
	ds_write2st64_b32 v132, v162, v164 offset0:48 offset1:56
	ds_write2st64_b32 v132, v166, v168 offset0:64 offset1:72
	ds_write2st64_b32 v132, v170, v172 offset0:80 offset1:88
	ds_write2st64_b32 v132, v174, v176 offset0:96 offset1:104
	ds_write2st64_b32 v132, v178, v180 offset0:112 offset1:120
	ds_write2st64_b32 v132, v182, v184 offset0:128 offset1:136
	ds_write2st64_b32 v132, v186, v188 offset0:144 offset1:152
	ds_write2st64_b32 v132, v190, v196 offset0:160 offset1:168
	ds_write2st64_b32 v132, v198, v200 offset0:176 offset1:184
	ds_write2st64_b32 v132, v202, v204 offset0:192 offset1:200
	ds_write2st64_b32 v132, v206, v208 offset0:208 offset1:216
	ds_write2st64_b32 v132, v210, v212 offset0:224 offset1:232
	ds_write_b32 v132, v214 offset:61440
	v_readlane_b32 s12, v255, 2
	v_readlane_b32 s13, v255, 3
	s_and_b64 vcc, exec, s[12:13]
	s_cbranch_vccnz .LBB0_847
	v_lshlrev_b64 v[6:7], 2, v[8:9]
	v_lshl_add_u64 v[2:3], s[14:15], 0, v[6:7]
	v_lshl_add_u64 v[4:5], s[34:35], 0, v[6:7]
	v_lshl_add_u64 v[6:7], s[46:47], 0, v[6:7]
	global_load_dwordx2 v[2:3], v[2:3], off
	v_readlane_b32 s12, v254, 59
	global_load_dwordx2 v[4:5], v[4:5], off
	s_mul_i32 s12, s7, s12
	global_load_dwordx2 v[6:7], v[6:7], off
	v_and_b32_e32 v12, 63, v10
	v_lshlrev_b64 v[10:11], 1, v[8:9]
	s_lshl_b32 s12, s12, 4
	v_lshl_add_u64 v[8:9], s[48:49], 0, v[10:11]
	v_lshl_add_u32 v133, v12, 2, 0
	s_mov_b32 s18, 0
	v_cmp_eq_u32_e64 s[40:41], 0, v12
	v_lshl_add_u64 v[10:11], s[50:51], 0, v[10:11]
	s_or_b32 s14, s12, 15
	s_branch .LBB0_745

; __device__ __forceinline__ float bf_lo(unsigned u) { return __uint_as_float(u << 16); }
; __device__ __forceinline__ float bf_hi(unsigned u) { return __uint_as_float(u & 0xffff0000u); }
; __device__ __forceinline__ void conv_run(LAS unsigned char* lds, const bf16_t* AG, bf16_t* CA, const float* cw, const float* cb, const float* lng, const float* lnb, int unit0, int nun, const int wave_s) {
;     ...
;         if (u == 0) {
; #pragma unroll
;             for (int i = 0; i < 46; ++i) { const int s = s0 - 15 + i;
;                 if (s >= 0 && s < SEQ) { const unsigned v = *(const unsigned*)(AG + (size_t)(b * SEQ + s) * DM + c); in[i] = (f32x2){bf_lo(v), bf_hi(v)}; } else in[i] = (f32x2){0.f, 0.f}; }
.LBB0_748:
	s_add_i32 s13, s39, s18
	s_add_i32 s12, s14, -15
	s_ashr_i32 s15, s13, 7
	s_andn2_b64 vcc, exec, s[34:35]
	s_and_b32 s13, s12, 0x7f0
	s_cbranch_vccnz .LBB0_810
	s_add_i32 s20, s13, -15
	s_lshl_b32 s19, s15, 11
	v_mov_b32_e32 v90, 0
	s_cmpk_gt_u32 s20, 0x7ff
	v_mov_b32_e32 v104, 0
	v_mov_b32_e32 v105, 0
	s_cbranch_scc1 .LBB0_751
	s_or_b32 s20, s20, s19
	s_ashr_i32 s21, s20, 31
	s_lshl_b64 s[20:21], s[20:21], 11
	v_lshl_add_u64 v[12:13], v[8:9], 0, s[20:21]
	global_load_dword v104, v[12:13], off
.LBB0_751:
	s_add_i32 s20, s13, -14
	s_cmpk_gt_u32 s20, 0x7ff
	v_mov_b32_e32 v91, 0
	s_cbranch_scc1 .LBB0_753
	s_or_b32 s20, s20, s19
	s_ashr_i32 s21, s20, 31
	s_lshl_b64 s[20:21], s[20:21], 11
	v_lshl_add_u64 v[12:13], v[8:9], 0, s[20:21]
	global_load_dword v90, v[12:13], off
.LBB0_753:
	s_add_i32 s20, s13, -13
	v_mov_b32_e32 v92, 0
	s_cmpk_gt_u32 s20, 0x7ff
	v_mov_b32_e32 v106, 0
	v_mov_b32_e32 v107, 0
	s_cbranch_scc1 .LBB0_755
	s_or_b32 s20, s20, s19
	s_ashr_i32 s21, s20, 31
	s_lshl_b64 s[20:21], s[20:21], 11
	v_lshl_add_u64 v[12:13], v[8:9], 0, s[20:21]
	global_load_dword v106, v[12:13], off
.LBB0_755:
	s_add_i32 s20, s13, -12
	s_cmpk_gt_u32 s20, 0x7ff
	v_mov_b32_e32 v93, 0
	s_cbranch_scc1 .LBB0_757
	s_or_b32 s20, s20, s19
	s_ashr_i32 s21, s20, 31
	s_lshl_b64 s[20:21], s[20:21], 11
	v_lshl_add_u64 v[12:13], v[8:9], 0, s[20:21]
	global_load_dword v92, v[12:13], off
.LBB0_757:
	s_add_i32 s20, s13, -11
	v_mov_b32_e32 v94, 0
	s_cmpk_gt_u32 s20, 0x7ff
	v_mov_b32_e32 v110, 0
	v_mov_b32_e32 v111, 0
	s_cbranch_scc1 .LBB0_759
	s_or_b32 s20, s20, s19
	s_ashr_i32 s21, s20, 31
	s_lshl_b64 s[20:21], s[20:21], 11
	v_lshl_add_u64 v[12:13], v[8:9], 0, s[20:21]
	global_load_dword v110, v[12:13], off
.LBB0_759:
	s_add_i32 s20, s13, -10
	s_cmpk_gt_u32 s20, 0x7ff
	v_mov_b32_e32 v95, 0
	s_cbranch_scc1 .LBB0_761
	s_or_b32 s20, s20, s19
	s_ashr_i32 s21, s20, 31
	s_lshl_b64 s[20:21], s[20:21], 11
	v_lshl_add_u64 v[12:13], v[8:9], 0, s[20:21]
	global_load_dword v94, v[12:13], off
.LBB0_761:
	s_add_i32 s20, s13, -9
	v_mov_b32_e32 v96, 0
	s_cmpk_gt_u32 s20, 0x7ff
	v_mov_b32_e32 v112, 0
	v_mov_b32_e32 v113, 0
	s_cbranch_scc1 .LBB0_763
	s_or_b32 s20, s20, s19
	s_ashr_i32 s21, s20, 31
	s_lshl_b64 s[20:21], s[20:21], 11
	v_lshl_add_u64 v[12:13], v[8:9], 0, s[20:21]
	global_load_dword v112, v[12:13], off
.LBB0_763:
	s_add_i32 s20, s13, -8
	s_cmpk_gt_u32 s20, 0x7ff
	v_mov_b32_e32 v97, 0
	s_cbranch_scc1 .LBB0_765
	s_or_b32 s20, s20, s19
	s_ashr_i32 s21, s20, 31
	s_lshl_b64 s[20:21], s[20:21], 11
	v_lshl_add_u64 v[12:13], v[8:9], 0, s[20:21]
	global_load_dword v96, v[12:13], off
.LBB0_765:
	s_add_i32 s20, s13, -7
	v_mov_b32_e32 v98, 0
	s_cmpk_gt_u32 s20, 0x7ff
	v_mov_b32_e32 v114, 0
	v_mov_b32_e32 v115, 0
	s_cbranch_scc1 .LBB0_767
	s_or_b32 s20, s20, s19
	s_ashr_i32 s21, s20, 31
	s_lshl_b64 s[20:21], s[20:21], 11
	v_lshl_add_u64 v[12:13], v[8:9], 0, s[20:21]
	global_load_dword v114, v[12:13], off
.LBB0_767:
	s_add_i32 s20, s13, -6
	s_cmpk_gt_u32 s20, 0x7ff
	v_mov_b32_e32 v99, 0
	s_cbranch_scc1 .LBB0_769
	s_or_b32 s20, s20, s19
	s_ashr_i32 s21, s20, 31
	s_lshl_b64 s[20:21], s[20:21], 11
	v_lshl_add_u64 v[12:13], v[8:9], 0, s[20:21]
	global_load_dword v98, v[12:13], off
.LBB0_769:
	s_add_i32 s20, s13, -5
	v_mov_b32_e32 v100, 0
	s_cmpk_gt_u32 s20, 0x7ff
	v_mov_b32_e32 v116, 0
	v_mov_b32_e32 v117, 0
	s_cbranch_scc1 .LBB0_771
	s_or_b32 s20, s20, s19
	s_ashr_i32 s21, s20, 31
	s_lshl_b64 s[20:21], s[20:21], 11
	v_lshl_add_u64 v[12:13], v[8:9], 0, s[20:21]
	global_load_dword v116, v[12:13], off
.LBB0_771:
	s_add_i32 s20, s13, -4
	s_cmpk_gt_u32 s20, 0x7ff
	v_mov_b32_e32 v101, 0
	s_cbranch_scc1 .LBB0_773
	s_or_b32 s20, s20, s19
	s_ashr_i32 s21, s20, 31
	s_lshl_b64 s[20:21], s[20:21], 11
	v_lshl_add_u64 v[12:13], v[8:9], 0, s[20:21]
	global_load_dword v100, v[12:13], off
.LBB0_773:
	s_add_i32 s20, s13, -3
	v_mov_b32_e32 v102, 0
	s_cmpk_gt_u32 s20, 0x7ff
	v_mov_b32_e32 v118, 0
	v_mov_b32_e32 v119, 0
	s_cbranch_scc1 .LBB0_775
	s_or_b32 s20, s20, s19
	s_ashr_i32 s21, s20, 31
	s_lshl_b64 s[20:21], s[20:21], 11
	v_lshl_add_u64 v[12:13], v[8:9], 0, s[20:21]
	global_load_dword v118, v[12:13], off
.LBB0_775:
	s_add_i32 s20, s13, -2
	s_cmpk_gt_u32 s20, 0x7ff
	v_mov_b32_e32 v103, 0
	s_cbranch_scc1 .LBB0_777
	s_or_b32 s20, s20, s19
	s_ashr_i32 s21, s20, 31
	s_lshl_b64 s[20:21], s[20:21], 11
	v_lshl_add_u64 v[12:13], v[8:9], 0, s[20:21]
	global_load_dword v102, v[12:13], off
.LBB0_777:
	s_add_i32 s20, s13, -1
	v_mov_b32_e32 v12, 0
	s_cmpk_gt_u32 s20, 0x7ff
	v_mov_b32_e32 v76, 0
	v_mov_b32_e32 v77, 0
	s_cbranch_scc1 .LBB0_779
	s_or_b32 s20, s20, s19
	s_ashr_i32 s21, s20, 31
	s_lshl_b64 s[20:21], s[20:21], 11
	v_lshl_add_u64 v[14:15], v[8:9], 0, s[20:21]
	global_load_dword v76, v[14:15], off
; __device__ __forceinline__ float bf_lo(unsigned u) { return __uint_as_float(u << 16); }
; __device__ __forceinline__ float bf_hi(unsigned u) { return __uint_as_float(u & 0xffff0000u); }
; __device__ __forceinline__ void conv_run(LAS unsigned char* lds, const bf16_t* AG, bf16_t* CA, const float* cw, const float* cb, const float* lng, const float* lnb, int unit0, int nun, const int wave_s) {
;     ...
;             for (int i = 0; i < 46; ++i) { const int s = s0 - 15 + i;
;                 if (s >= 0 && s < SEQ) { const unsigned v = *(const unsigned*)(AG + (size_t)(b * SEQ + s) * DM + c); in[i] = (f32x2){bf_lo(v), bf_hi(v)}; } else in[i] = (f32x2){0.f, 0.f}; }
.LBB0_779:
	s_or_b32 s34, s13, s19
	s_ashr_i32 s35, s34, 31
	s_lshl_b64 s[20:21], s[34:35], 11
	v_lshl_add_u64 v[14:15], v[8:9], 0, s[20:21]
	s_or_b32 s20, s34, 1
	s_ashr_i32 s21, s20, 31
	s_lshl_b64 s[20:21], s[20:21], 11
	global_load_dword v26, v[14:15], off
	v_lshl_add_u64 v[14:15], v[8:9], 0, s[20:21]
	s_or_b32 s20, s34, 2
	s_ashr_i32 s21, s20, 31
	s_lshl_b64 s[20:21], s[20:21], 11
	global_load_dword v27, v[14:15], off
	v_lshl_add_u64 v[14:15], v[8:9], 0, s[20:21]
	s_or_b32 s20, s34, 3
	s_ashr_i32 s21, s20, 31
	s_lshl_b64 s[20:21], s[20:21], 11
	global_load_dword v44, v[14:15], off
	v_lshl_add_u64 v[14:15], v[8:9], 0, s[20:21]
	s_or_b32 s20, s34, 4
	s_ashr_i32 s21, s20, 31
	s_lshl_b64 s[20:21], s[20:21], 11
	global_load_dword v45, v[14:15], off
	v_lshl_add_u64 v[14:15], v[8:9], 0, s[20:21]
	s_or_b32 s20, s34, 5
	s_ashr_i32 s21, s20, 31
	s_lshl_b64 s[20:21], s[20:21], 11
	global_load_dword v46, v[14:15], off
	v_lshl_add_u64 v[14:15], v[8:9], 0, s[20:21]
	s_or_b32 s20, s34, 6
	s_ashr_i32 s21, s20, 31
	s_lshl_b64 s[20:21], s[20:21], 11
	global_load_dword v47, v[14:15], off
	v_lshl_add_u64 v[14:15], v[8:9], 0, s[20:21]
	s_or_b32 s20, s34, 7
	s_ashr_i32 s21, s20, 31
	s_lshl_b64 s[20:21], s[20:21], 11
	global_load_dword v48, v[14:15], off
	v_lshl_add_u64 v[14:15], v[8:9], 0, s[20:21]
	s_or_b32 s20, s34, 8
	s_ashr_i32 s21, s20, 31
	s_lshl_b64 s[20:21], s[20:21], 11
	global_load_dword v49, v[14:15], off
	v_lshl_add_u64 v[14:15], v[8:9], 0, s[20:21]
	s_or_b32 s20, s34, 9
	s_ashr_i32 s21, s20, 31
	s_lshl_b64 s[20:21], s[20:21], 11
	global_load_dword v50, v[14:15], off
	v_lshl_add_u64 v[14:15], v[8:9], 0, s[20:21]
	s_or_b32 s20, s34, 10
	s_ashr_i32 s21, s20, 31
	s_lshl_b64 s[20:21], s[20:21], 11
	global_load_dword v51, v[14:15], off
	v_lshl_add_u64 v[14:15], v[8:9], 0, s[20:21]
	s_or_b32 s20, s34, 11
	s_ashr_i32 s21, s20, 31
	s_lshl_b64 s[20:21], s[20:21], 11
	global_load_dword v52, v[14:15], off
	v_lshl_add_u64 v[14:15], v[8:9], 0, s[20:21]
	s_or_b32 s20, s34, 12
	s_ashr_i32 s21, s20, 31
	s_lshl_b64 s[20:21], s[20:21], 11
	global_load_dword v53, v[14:15], off
	v_lshl_add_u64 v[14:15], v[8:9], 0, s[20:21]
	s_or_b32 s20, s34, 13
	s_ashr_i32 s21, s20, 31
	s_lshl_b64 s[20:21], s[20:21], 11
	global_load_dword v54, v[14:15], off
	v_lshl_add_u64 v[14:15], v[8:9], 0, s[20:21]
	s_or_b32 s20, s34, 14
	s_ashr_i32 s21, s20, 31
	s_lshl_b64 s[20:21], s[20:21], 11
	global_load_dword v55, v[14:15], off
	v_lshl_add_u64 v[14:15], v[8:9], 0, s[20:21]
	s_or_b32 s20, s34, 15
	s_ashr_i32 s21, s20, 31
	s_lshl_b64 s[20:21], s[20:21], 11
	global_load_dword v56, v[14:15], off
	v_lshl_add_u64 v[14:15], v[8:9], 0, s[20:21]
	global_load_dword v57, v[14:15], off
	s_cmpk_eq_i32 s13, 0x7f0
	v_mov_b32_e32 v13, 0
	s_cbranch_scc1 .LBB0_781
	s_add_i32 s20, s13, s19
	s_add_i32 s20, s20, 16
	s_ashr_i32 s21, s20, 31
	s_lshl_b64 s[20:21], s[20:21], 11
	v_lshl_add_u64 v[12:13], v[8:9], 0, s[20:21]
	global_load_dword v13, v[12:13], off
.LBB0_781:
	v_mov_b32_e32 v16, 0
	s_cmpk_gt_u32 s13, 0x7ee
	v_mov_b32_e32 v14, 0
	v_mov_b32_e32 v15, 0
	s_cbranch_scc1 .LBB0_783
	s_add_i32 s20, s13, s19
	s_add_i32 s20, s20, 17
	s_ashr_i32 s21, s20, 31
	s_lshl_b64 s[20:21], s[20:21], 11
	v_lshl_add_u64 v[14:15], v[8:9], 0, s[20:21]
	global_load_dword v15, v[14:15], off
.LBB0_783:
	s_cmpk_gt_u32 s13, 0x7ed
	v_mov_b32_e32 v17, 0
	s_cbranch_scc1 .LBB0_785
	s_add_i32 s20, s13, s19
	s_add_i32 s20, s20, 18
	s_ashr_i32 s21, s20, 31
	s_lshl_b64 s[20:21], s[20:21], 11
	v_lshl_add_u64 v[16:17], v[8:9], 0, s[20:21]
	global_load_dword v17, v[16:17], off
.LBB0_785:
	v_mov_b32_e32 v20, 0
	s_cmpk_gt_u32 s13, 0x7ec
	v_mov_b32_e32 v18, 0
	v_mov_b32_e32 v19, 0
	s_cbranch_scc1 .LBB0_787
	s_add_i32 s20, s13, s19
	s_add_i32 s20, s20, 19
	s_ashr_i32 s21, s20, 31
	s_lshl_b64 s[20:21], s[20:21], 11
	v_lshl_add_u64 v[18:19], v[8:9], 0, s[20:21]
	global_load_dword v19, v[18:19], off
.LBB0_787:
	s_cmpk_gt_u32 s13, 0x7eb
	v_mov_b32_e32 v21, 0
	s_cbranch_scc1 .LBB0_789
	s_add_i32 s20, s13, s19
	s_add_i32 s20, s20, 20
	s_ashr_i32 s21, s20, 31
	s_lshl_b64 s[20:21], s[20:21], 11
	v_lshl_add_u64 v[20:21], v[8:9], 0, s[20:21]
	global_load_dword v21, v[20:21], off
.LBB0_789:
	v_mov_b32_e32 v24, 0
	s_cmpk_gt_u32 s13, 0x7ea
	v_mov_b32_e32 v22, 0
	v_mov_b32_e32 v23, 0
	s_cbranch_scc1 .LBB0_791
	s_add_i32 s20, s13, s19
	s_add_i32 s20, s20, 21
	s_ashr_i32 s21, s20, 31
	s_lshl_b64 s[20:21], s[20:21], 11
	v_lshl_add_u64 v[22:23], v[8:9], 0, s[20:21]
	global_load_dword v23, v[22:23], off
.LBB0_791:
	s_cmpk_gt_u32 s13, 0x7e9
	v_mov_b32_e32 v25, 0
	s_cbranch_scc1 .LBB0_793
	s_add_i32 s20, s13, s19
	s_add_i32 s20, s20, 22
	s_ashr_i32 s21, s20, 31
	s_lshl_b64 s[20:21], s[20:21], 11
	v_lshl_add_u64 v[24:25], v[8:9], 0, s[20:21]
	global_load_dword v25, v[24:25], off
.LBB0_793:
	v_mov_b32_e32 v30, 0
	s_cmpk_gt_u32 s13, 0x7e8
	v_mov_b32_e32 v28, 0
	v_mov_b32_e32 v29, 0
	s_cbranch_scc1 .LBB0_795
	s_add_i32 s20, s13, s19
	s_add_i32 s20, s20, 23
	s_ashr_i32 s21, s20, 31
	s_lshl_b64 s[20:21], s[20:21], 11
	v_lshl_add_u64 v[28:29], v[8:9], 0, s[20:21]
	global_load_dword v29, v[28:29], off
.LBB0_795:
	s_cmpk_gt_u32 s13, 0x7e7
	v_mov_b32_e32 v31, 0
	s_cbranch_scc1 .LBB0_797
	s_add_i32 s20, s13, s19
	s_add_i32 s20, s20, 24
	s_ashr_i32 s21, s20, 31
	s_lshl_b64 s[20:21], s[20:21], 11
	v_lshl_add_u64 v[30:31], v[8:9], 0, s[20:21]
	global_load_dword v31, v[30:31], off
; __device__ __forceinline__ float bf_lo(unsigned u) { return __uint_as_float(u << 16); }
; __device__ __forceinline__ float bf_hi(unsigned u) { return __uint_as_float(u & 0xffff0000u); }
; __device__ __forceinline__ void conv_run(LAS unsigned char* lds, const bf16_t* AG, bf16_t* CA, const float* cw, const float* cb, const float* lng, const float* lnb, int unit0, int nun, const int wave_s) {
;     ...
;             for (int i = 0; i < 46; ++i) { const int s = s0 - 15 + i;
;                 if (s >= 0 && s < SEQ) { const unsigned v = *(const unsigned*)(AG + (size_t)(b * SEQ + s) * DM + c); in[i] = (f32x2){bf_lo(v), bf_hi(v)}; } else in[i] = (f32x2){0.f, 0.f}; }
.LBB0_797:
	v_mov_b32_e32 v34, 0
	s_cmpk_gt_u32 s13, 0x7e6
	v_mov_b32_e32 v32, 0
	v_mov_b32_e32 v33, 0
	s_cbranch_scc1 .LBB0_799
	s_add_i32 s20, s13, s19
	s_add_i32 s20, s20, 25
	s_ashr_i32 s21, s20, 31
	s_lshl_b64 s[20:21], s[20:21], 11
	v_lshl_add_u64 v[32:33], v[8:9], 0, s[20:21]
	global_load_dword v33, v[32:33], off
.LBB0_799:
	s_cmpk_gt_u32 s13, 0x7e5
	v_mov_b32_e32 v35, 0
	s_cbranch_scc1 .LBB0_801
	s_add_i32 s20, s13, s19
	s_add_i32 s20, s20, 26
	s_ashr_i32 s21, s20, 31
	s_lshl_b64 s[20:21], s[20:21], 11
	v_lshl_add_u64 v[34:35], v[8:9], 0, s[20:21]
	global_load_dword v35, v[34:35], off
.LBB0_801:
	v_mov_b32_e32 v38, 0
	s_cmpk_gt_u32 s13, 0x7e4
	v_mov_b32_e32 v36, 0
	v_mov_b32_e32 v37, 0
	s_cbranch_scc1 .LBB0_803
	s_add_i32 s20, s13, s19
	s_add_i32 s20, s20, 27
	s_ashr_i32 s21, s20, 31
	s_lshl_b64 s[20:21], s[20:21], 11
	v_lshl_add_u64 v[36:37], v[8:9], 0, s[20:21]
	global_load_dword v37, v[36:37], off
.LBB0_803:
	s_cmpk_gt_u32 s13, 0x7e3
	v_mov_b32_e32 v39, 0
	s_cbranch_scc1 .LBB0_805
	s_add_i32 s20, s13, s19
	s_add_i32 s20, s20, 28
	s_ashr_i32 s21, s20, 31
	s_lshl_b64 s[20:21], s[20:21], 11
	v_lshl_add_u64 v[38:39], v[8:9], 0, s[20:21]
	global_load_dword v39, v[38:39], off
.LBB0_805:
	v_mov_b32_e32 v43, 0
	s_cmpk_gt_u32 s13, 0x7e2
	v_mov_b32_e32 v40, 0
	v_mov_b32_e32 v41, 0
	s_cbranch_scc1 .LBB0_807
	s_add_i32 s20, s13, s19
	s_add_i32 s20, s20, 29
	s_ashr_i32 s21, s20, 31
	s_lshl_b64 s[20:21], s[20:21], 11
	v_lshl_add_u64 v[40:41], v[8:9], 0, s[20:21]
	global_load_dword v41, v[40:41], off
.LBB0_807:
	s_cmpk_gt_u32 s13, 0x7e1
	v_mov_b32_e32 v42, 0
	s_cbranch_scc1 .LBB0_809
	s_add_i32 s19, s13, s19
	s_add_i32 s20, s19, 30
	s_ashr_i32 s21, s20, 31
	s_lshl_b64 s[20:21], s[20:21], 11
	v_lshl_add_u64 v[42:43], v[8:9], 0, s[20:21]
	global_load_dword v43, v[42:43], off
.LBB0_809:
	s_waitcnt vmcnt(0)
	v_and_b32_e32 v105, 0xffff0000, v104
	v_lshlrev_b32_e32 v104, 16, v104
	v_and_b32_e32 v91, 0xffff0000, v90
	v_lshlrev_b32_e32 v90, 16, v90
	v_and_b32_e32 v107, 0xffff0000, v106
	v_lshlrev_b32_e32 v106, 16, v106
	v_and_b32_e32 v93, 0xffff0000, v92
	v_lshlrev_b32_e32 v92, 16, v92
	v_and_b32_e32 v111, 0xffff0000, v110
	v_lshlrev_b32_e32 v110, 16, v110
	v_and_b32_e32 v95, 0xffff0000, v94
	v_lshlrev_b32_e32 v94, 16, v94
	v_and_b32_e32 v113, 0xffff0000, v112
	v_lshlrev_b32_e32 v112, 16, v112
	v_and_b32_e32 v97, 0xffff0000, v96
	v_lshlrev_b32_e32 v96, 16, v96
	v_and_b32_e32 v115, 0xffff0000, v114
	v_lshlrev_b32_e32 v114, 16, v114
	v_and_b32_e32 v99, 0xffff0000, v98
	v_lshlrev_b32_e32 v98, 16, v98
	v_and_b32_e32 v117, 0xffff0000, v116
	v_lshlrev_b32_e32 v116, 16, v116
	v_and_b32_e32 v101, 0xffff0000, v100
	v_lshlrev_b32_e32 v100, 16, v100
	v_and_b32_e32 v119, 0xffff0000, v118
	v_lshlrev_b32_e32 v118, 16, v118
	v_and_b32_e32 v103, 0xffff0000, v102
	v_lshlrev_b32_e32 v102, 16, v102
	v_and_b32_e32 v77, 0xffff0000, v76
	v_lshlrev_b32_e32 v76, 16, v76
	v_lshlrev_b32_e32 v12, 16, v13
	v_and_b32_e32 v13, 0xffff0000, v13
	v_lshlrev_b32_e32 v14, 16, v15
	v_and_b32_e32 v15, 0xffff0000, v15
	v_lshlrev_b32_e32 v16, 16, v17
	v_and_b32_e32 v17, 0xffff0000, v17
	v_lshlrev_b32_e32 v18, 16, v19
	v_and_b32_e32 v19, 0xffff0000, v19
	v_lshlrev_b32_e32 v20, 16, v21
	v_and_b32_e32 v21, 0xffff0000, v21
	v_lshlrev_b32_e32 v22, 16, v23
	v_and_b32_e32 v23, 0xffff0000, v23
	v_lshlrev_b32_e32 v24, 16, v25
	v_and_b32_e32 v25, 0xffff0000, v25
	v_lshlrev_b32_e32 v28, 16, v29
	v_and_b32_e32 v29, 0xffff0000, v29
	v_lshlrev_b32_e32 v30, 16, v31
	v_and_b32_e32 v31, 0xffff0000, v31
	v_lshlrev_b32_e32 v32, 16, v33
	v_and_b32_e32 v33, 0xffff0000, v33
	v_lshlrev_b32_e32 v34, 16, v35
	v_and_b32_e32 v35, 0xffff0000, v35
	v_lshlrev_b32_e32 v36, 16, v37
	v_and_b32_e32 v37, 0xffff0000, v37
	v_lshlrev_b32_e32 v38, 16, v39
	v_and_b32_e32 v39, 0xffff0000, v39
	v_lshlrev_b32_e32 v40, 16, v41
	v_and_b32_e32 v41, 0xffff0000, v41
	v_lshlrev_b32_e32 v42, 16, v43
	v_and_b32_e32 v43, 0xffff0000, v43
	s_waitcnt vmcnt(15)
	v_lshlrev_b32_e32 v130, 16, v26
	v_and_b32_e32 v131, 0xffff0000, v26
	s_waitcnt vmcnt(14)
	v_lshlrev_b32_e32 v128, 16, v27
	v_and_b32_e32 v129, 0xffff0000, v27
	s_waitcnt vmcnt(13)
	v_lshlrev_b32_e32 v126, 16, v44
	v_and_b32_e32 v127, 0xffff0000, v44
	s_waitcnt vmcnt(12)
	v_lshlrev_b32_e32 v124, 16, v45
	v_and_b32_e32 v125, 0xffff0000, v45
	s_waitcnt vmcnt(11)
	v_lshlrev_b32_e32 v122, 16, v46
	v_and_b32_e32 v123, 0xffff0000, v46
	s_waitcnt vmcnt(10)
	v_lshlrev_b32_e32 v120, 16, v47
	v_and_b32_e32 v121, 0xffff0000, v47
	s_waitcnt vmcnt(9)
	v_lshlrev_b32_e32 v108, 16, v48
	v_and_b32_e32 v109, 0xffff0000, v48
	s_waitcnt vmcnt(8)
	v_lshlrev_b32_e32 v88, 16, v49
	v_and_b32_e32 v89, 0xffff0000, v49
	s_waitcnt vmcnt(7)
	v_lshlrev_b32_e32 v86, 16, v50
	v_and_b32_e32 v87, 0xffff0000, v50
	s_waitcnt vmcnt(6)
	v_lshlrev_b32_e32 v84, 16, v51
	v_and_b32_e32 v85, 0xffff0000, v51
	s_waitcnt vmcnt(5)
	v_lshlrev_b32_e32 v82, 16, v52
	v_and_b32_e32 v83, 0xffff0000, v52
	s_waitcnt vmcnt(4)
	v_lshlrev_b32_e32 v80, 16, v53
	v_and_b32_e32 v81, 0xffff0000, v53
	s_waitcnt vmcnt(3)
	v_lshlrev_b32_e32 v78, 16, v54
	v_and_b32_e32 v79, 0xffff0000, v54
	s_waitcnt vmcnt(2)
	v_lshlrev_b32_e32 v74, 16, v55
	v_and_b32_e32 v75, 0xffff0000, v55
	s_waitcnt vmcnt(1)
	v_lshlrev_b32_e32 v72, 16, v56
	v_and_b32_e32 v73, 0xffff0000, v56
	s_waitcnt vmcnt(0)
	v_lshlrev_b32_e32 v26, 16, v57
	v_and_b32_e32 v27, 0xffff0000, v57

; #define LAS __attribute__((address_space(3)))
; __device__ __forceinline__ unsigned cvt_pk_bf16(float lo, float hi) { const f32x2 v = {lo, hi}; const bf16x2_t b = __builtin_convertvector(v, bf16x2_t); return __builtin_bit_cast(unsigned, b); }
; __device__ __forceinline__ float bf_lo(unsigned u) { return __uint_as_float(u << 16); }
; __device__ __forceinline__ float bf_hi(unsigned u) { return __uint_as_float(u & 0xffff0000u); }
; template <bool STORE> __device__ __forceinline__ void sgu_unit(LAS unsigned char* lds, const bf16_t* GEL, const float* STAT, bf16_t* GU, const float* sw, const float* sb, const float* lng, const float* lnb, int unit, const int wave_s) {
;     ...
;     for (int i = 0; i < 8; ++i) { const int id = tid + 512 * i, t = id >> 5, s4 = (id & 31) * 4; const f32x4 v = *(const f32x4*)(sw + (size_t)g * 16384 + t * 128 + s4);
;         u32x2 w; w.x = cvt_pk_bf16(v[0], v[1]); w.y = cvt_pk_bf16(v[2], v[3]); *(LAS u32x2*)(lds + SG_WL + t * 272 + s4 * 2) = w; }
;     __syncthreads();
; #pragma unroll
;     for (int i = 0; i < 4; ++i) { const int id = tid + 512 * i, s = id >> 4, cc = (id & 15) * 8; const u32x4 v = gv4[i];
;         const float mean = st[2 * s], rstd = st[2 * s + 1];
;         const f32x4 g0 = *(const f32x4*)(lng + c0 + cc), g1 = *(const f32x4*)(lng + c0 + cc + 4), b0 = *(const f32x4*)(lnb + c0 + cc), b1 = *(const f32x4*)(lnb + c0 + cc + 4);
;         float x[8] = {bf_lo(v.x), bf_hi(v.x), bf_lo(v.y), bf_hi(v.y), bf_lo(v.z), bf_hi(v.z), bf_lo(v.w), bf_hi(v.w)};
; #pragma unroll
;         for (int k = 0; k < 8; ++k) { const float gg = k < 4 ? g0[k & 3] : g1[k & 3], bb = k < 4 ? b0[k & 3] : b1[k & 3]; const float y = (x[k] - mean) * rstd * gg + bb;
;             *(LAS bf16_t*)(lds + SG_GL + (cc + k) * 272 + s * 2) = (bf16_t)(cvt_pk_bf16(y, 0.f) & 0xffffu); } }
.LBB0_849:
	s_or_b64 exec, exec, s[34:35]
	v_lshlrev_b32_e32 v0, 2, v34
	s_lshl_b32 s34, s45, 16
	v_and_b32_e32 v7, 0x7c, v0
	s_add_u32 s34, s16, s34
	s_addc_u32 s35, s18, 0
	v_lshlrev_b32_e32 v0, 2, v7
	v_lshl_add_u64 v[12:13], s[34:35], 0, v[0:1]
	v_lshl_add_u32 v0, v7, 1, 0
	v_ashrrev_i32_e32 v7, 5, v6
	v_lshlrev_b32_e32 v8, 7, v7
	v_ashrrev_i32_e32 v9, 31, v8
	v_lshl_add_u64 v[8:9], v[8:9], 2, v[12:13]
	global_load_dwordx4 v[196:199], v[8:9], off
	v_mov_b32_e32 v228, v7
	s_movk_i32 s45, 0x110
	v_ashrrev_i32_e32 v229, 5, v37
	v_lshlrev_b32_e32 v8, 7, v229
	v_ashrrev_i32_e32 v9, 31, v8
	v_lshl_add_u64 v[8:9], v[8:9], 2, v[12:13]
	global_load_dwordx4 v[200:203], v[8:9], off
	v_ashrrev_i32_e32 v230, 5, v36
	v_lshlrev_b32_e32 v8, 7, v230
	v_ashrrev_i32_e32 v9, 31, v8
	v_lshl_add_u64 v[8:9], v[8:9], 2, v[12:13]
	global_load_dwordx4 v[204:207], v[8:9], off
	v_ashrrev_i32_e32 v231, 5, v35
	v_lshlrev_b32_e32 v8, 7, v231
	v_ashrrev_i32_e32 v9, 31, v8
	v_lshl_add_u64 v[8:9], v[8:9], 2, v[12:13]
	global_load_dwordx4 v[208:211], v[8:9], off
	v_add_u32_e32 v232, 0x800, v6
	v_ashrrev_i32_e32 v232, 5, v232
	v_lshlrev_b32_e32 v8, 7, v232
	v_ashrrev_i32_e32 v9, 31, v8
	v_lshl_add_u64 v[8:9], v[8:9], 2, v[12:13]
	global_load_dwordx4 v[212:215], v[8:9], off
	v_add_u32_e32 v233, 0xa00, v6
	v_ashrrev_i32_e32 v233, 5, v233
	v_lshlrev_b32_e32 v8, 7, v233
	v_ashrrev_i32_e32 v9, 31, v8
	v_lshl_add_u64 v[8:9], v[8:9], 2, v[12:13]
	global_load_dwordx4 v[216:219], v[8:9], off
	v_add_u32_e32 v234, 0xc00, v6
	v_ashrrev_i32_e32 v234, 5, v234
	v_lshlrev_b32_e32 v8, 7, v234
	v_ashrrev_i32_e32 v9, 31, v8
	v_lshl_add_u64 v[8:9], v[8:9], 2, v[12:13]
	global_load_dwordx4 v[220:223], v[8:9], off
	v_add_u32_e32 v235, 0xe00, v6
	v_ashrrev_i32_e32 v235, 5, v235
	v_lshlrev_b32_e32 v8, 7, v235
	v_ashrrev_i32_e32 v9, 31, v8
	v_lshl_add_u64 v[8:9], v[8:9], 2, v[12:13]
	global_load_dwordx4 v[224:227], v[8:9], off
	s_waitcnt vmcnt(11)
	v_lshlrev_b32_e32 v42, 16, v31
	v_and_b32_e32 v31, 0xffff0000, v31
	v_lshlrev_b32_e32 v43, 16, v32
	v_and_b32_e32 v32, 0xffff0000, v32
	v_lshlrev_b32_e32 v44, 16, v33
	v_and_b32_e32 v33, 0xffff0000, v33
	v_bfe_u32 v46, v34, 5, 1
	v_ashrrev_i32_e32 v6, 3, v6
	v_and_b32_e32 v39, -2, v6
	v_lshl_or_b32 v6, v6, 2, 4
	s_waitcnt vmcnt(7)
	v_cvt_pk_bf16_f32 v8, v196, v197
	v_cvt_pk_bf16_f32 v9, v198, v199
	v_mad_u64_u32 v[10:11], s[34:35], v228, s45, v[0:1]
	ds_write_b64 v10, v[8:9]
	s_waitcnt vmcnt(6)
	v_cvt_pk_bf16_f32 v8, v200, v201
	v_cvt_pk_bf16_f32 v9, v202, v203
	v_mad_u64_u32 v[10:11], s[34:35], v229, s45, v[0:1]
	ds_write_b64 v10, v[8:9]
	s_waitcnt vmcnt(5)
	v_cvt_pk_bf16_f32 v8, v204, v205
	v_cvt_pk_bf16_f32 v9, v206, v207
	v_mad_u64_u32 v[10:11], s[34:35], v230, s45, v[0:1]
	ds_write_b64 v10, v[8:9]
	s_waitcnt vmcnt(4)
	v_cvt_pk_bf16_f32 v8, v208, v209
	v_cvt_pk_bf16_f32 v9, v210, v211
	v_mad_u64_u32 v[10:11], s[34:35], v231, s45, v[0:1]
	ds_write_b64 v10, v[8:9]
	s_waitcnt vmcnt(3)
	v_cvt_pk_bf16_f32 v8, v212, v213
	v_cvt_pk_bf16_f32 v9, v214, v215
	v_mad_u64_u32 v[10:11], s[34:35], v232, s45, v[0:1]
	ds_write_b64 v10, v[8:9]
	s_waitcnt vmcnt(2)
	v_cvt_pk_bf16_f32 v8, v216, v217
	v_cvt_pk_bf16_f32 v9, v218, v219
	v_mad_u64_u32 v[10:11], s[34:35], v233, s45, v[0:1]
	ds_write_b64 v10, v[8:9]
	s_waitcnt vmcnt(1)
	v_cvt_pk_bf16_f32 v8, v220, v221
	v_cvt_pk_bf16_f32 v9, v222, v223
	v_mad_u64_u32 v[10:11], s[34:35], v234, s45, v[0:1]
	ds_write_b64 v10, v[8:9]
	s_waitcnt vmcnt(0)
	v_cvt_pk_bf16_f32 v8, v224, v225
	v_cvt_pk_bf16_f32 v9, v226, v227
	v_mad_u64_u32 v[10:11], s[34:35], v235, s45, v[0:1]
	ds_write_b64 v10, v[8:9]
	s_lshl_b32 s34, s44, 2
	s_add_u32 s46, s19, s34
	s_addc_u32 s47, s20, 0
	s_add_u32 s48, s21, s34
	s_addc_u32 s49, s28, 0
	s_add_i32 s34, 0, 0x11000
	v_lshlrev_b32_e32 v0, 2, v38
	v_lshl_add_u32 v7, v39, 2, s34
	v_add_u32_e32 v6, s34, v6
	s_waitcnt lgkmcnt(0)
	s_barrier
	ds_read_b32 v40, v7
	ds_read_b32 v41, v6
	global_load_dwordx4 v[6:9], v0, s[46:47] offset:16
	global_load_dwordx4 v[14:17], v0, s[46:47]
	global_load_dwordx4 v[10:13], v0, s[48:49] offset:16
	global_load_dwordx4 v[22:25], v0, s[48:49]
	v_lshlrev_b32_e32 v0, 16, v30
	v_and_b32_e32 v30, 0xffff0000, v30
	s_waitcnt lgkmcnt(1)
	v_sub_f32_e32 v0, v0, v40
	s_waitcnt lgkmcnt(0)
	v_mul_f32_e32 v0, v41, v0
	v_sub_f32_e32 v30, v30, v40
	v_mul_f32_e32 v30, v41, v30
	s_waitcnt vmcnt(0)
	v_fma_f32 v0, v0, v14, v22
	v_cvt_pk_bf16_f32 v45, v0, s0
	v_mul_u32_u24_e32 v0, 0x110, v38
	v_fma_f32 v30, v30, v15, v23
	v_add3_u32 v38, 0, v39, v0
	v_cvt_pk_bf16_f32 v30, v30, s0
	ds_write_b16 v38, v30 offset:35088
	v_sub_f32_e32 v30, v42, v40
	v_mul_f32_e32 v30, v41, v30
	v_fma_f32 v30, v30, v16, v24
	v_cvt_pk_bf16_f32 v30, v30, s0
	ds_write_b16 v38, v30 offset:35360
	v_sub_f32_e32 v30, v31, v40
	v_mul_f32_e32 v30, v41, v30
	v_fma_f32 v30, v30, v17, v25
	v_cvt_pk_bf16_f32 v30, v30, s0
	ds_write_b16 v38, v30 offset:35632
	v_sub_f32_e32 v30, v43, v40
	v_mul_f32_e32 v30, v41, v30
	v_fma_f32 v30, v30, v6, v10
	v_cvt_pk_bf16_f32 v30, v30, s0
	ds_write_b16 v38, v30 offset:35904
	v_sub_f32_e32 v30, v32, v40
	v_mul_f32_e32 v30, v41, v30
	v_fma_f32 v30, v30, v7, v11
	v_cvt_pk_bf16_f32 v30, v30, s0
	ds_write_b16 v38, v30 offset:36176
	v_sub_f32_e32 v30, v44, v40
	v_mul_f32_e32 v30, v41, v30
	v_fma_f32 v30, v30, v8, v12
	v_cvt_pk_bf16_f32 v30, v30, s0
	ds_write_b16 v38, v30 offset:36448
	v_sub_f32_e32 v30, v33, v40
	v_mul_f32_e32 v30, v41, v30
	v_fma_f32 v30, v30, v9, v13
	v_cvt_pk_bf16_f32 v30, v30, s0
	ds_write_b16 v38, v30 offset:36720
	v_ashrrev_i32_e32 v30, 3, v37
	v_and_b32_e32 v31, -2, v30
	v_lshl_add_u32 v32, v31, 2, s34
	v_lshl_or_b32 v30, v30, 2, 4
	ds_read_b32 v32, v32
	v_add_u32_e32 v30, s34, v30
	ds_read_b32 v30, v30
	v_lshlrev_b32_e32 v33, 16, v26
	v_and_b32_e32 v26, 0xffff0000, v26
	s_waitcnt lgkmcnt(1)
; #define LAS __attribute__((address_space(3)))
; __device__ __forceinline__ unsigned cvt_pk_bf16(float lo, float hi) { const f32x2 v = {lo, hi}; const bf16x2_t b = __builtin_convertvector(v, bf16x2_t); return __builtin_bit_cast(unsigned, b); }
; __device__ __forceinline__ float bf_lo(unsigned u) { return __uint_as_float(u << 16); }
; __device__ __forceinline__ float bf_hi(unsigned u) { return __uint_as_float(u & 0xffff0000u); }
; template <bool STORE> __device__ __forceinline__ void sgu_unit(LAS unsigned char* lds, const bf16_t* GEL, const float* STAT, bf16_t* GU, const float* sw, const float* sb, const float* lng, const float* lnb, int unit, const int wave_s) {
;     ...
;     for (int i = 0; i < 4; ++i) { const int id = tid + 512 * i, s = id >> 4, cc = (id & 15) * 8; const u32x4 v = gv4[i];
;         const float mean = st[2 * s], rstd = st[2 * s + 1];
;         const f32x4 g0 = *(const f32x4*)(lng + c0 + cc), g1 = *(const f32x4*)(lng + c0 + cc + 4), b0 = *(const f32x4*)(lnb + c0 + cc), b1 = *(const f32x4*)(lnb + c0 + cc + 4);
;         float x[8] = {bf_lo(v.x), bf_hi(v.x), bf_lo(v.y), bf_hi(v.y), bf_lo(v.z), bf_hi(v.z), bf_lo(v.w), bf_hi(v.w)};
; #pragma unroll
;         for (int k = 0; k < 8; ++k) { const float gg = k < 4 ? g0[k & 3] : g1[k & 3], bb = k < 4 ? b0[k & 3] : b1[k & 3]; const float y = (x[k] - mean) * rstd * gg + bb;
;             *(LAS bf16_t*)(lds + SG_GL + (cc + k) * 272 + s * 2) = (bf16_t)(cvt_pk_bf16(y, 0.f) & 0xffffu); } }
;     __syncthreads();
;     const int cb = wid & 3, th = wid >> 2, q = lane & 31, hi = lane >> 5;
	v_sub_f32_e32 v26, v26, v32
	v_lshlrev_b32_e32 v37, 16, v27
	s_waitcnt lgkmcnt(0)
	v_mul_f32_e32 v26, v30, v26
	v_fma_f32 v26, v15, v26, v23
	v_add3_u32 v31, 0, v31, v0
	v_cvt_pk_bf16_f32 v26, v26, s0
	ds_write_b16 v38, v45 offset:34816
	ds_write_b16 v31, v26 offset:35088
	v_sub_f32_e32 v26, v37, v32
	v_mul_f32_e32 v26, v30, v26
	v_fma_f32 v26, v16, v26, v24
	v_and_b32_e32 v27, 0xffff0000, v27
	v_cvt_pk_bf16_f32 v26, v26, s0
	ds_write_b16 v31, v26 offset:35360
	v_sub_f32_e32 v26, v27, v32
	v_mul_f32_e32 v26, v30, v26
	v_fma_f32 v26, v17, v26, v25
	v_lshlrev_b32_e32 v38, 16, v28
	v_cvt_pk_bf16_f32 v26, v26, s0
	ds_write_b16 v31, v26 offset:35632
	v_sub_f32_e32 v26, v38, v32
	v_mul_f32_e32 v26, v30, v26
	v_fma_f32 v26, v6, v26, v10
	v_and_b32_e32 v28, 0xffff0000, v28
	v_cvt_pk_bf16_f32 v26, v26, s0
	ds_write_b16 v31, v26 offset:35904
	v_sub_f32_e32 v26, v28, v32
	v_mul_f32_e32 v26, v30, v26
	v_fma_f32 v26, v7, v26, v11
	v_lshlrev_b32_e32 v39, 16, v29
	v_cvt_pk_bf16_f32 v26, v26, s0
	ds_write_b16 v31, v26 offset:36176
	v_sub_f32_e32 v26, v39, v32
	v_mul_f32_e32 v26, v30, v26
	v_fma_f32 v26, v8, v26, v12
	v_and_b32_e32 v29, 0xffff0000, v29
	v_cvt_pk_bf16_f32 v26, v26, s0
	ds_write_b16 v31, v26 offset:36448
	v_sub_f32_e32 v26, v29, v32
	v_mul_f32_e32 v26, v30, v26
	v_fma_f32 v26, v9, v26, v13
	v_cvt_pk_bf16_f32 v26, v26, s0
	ds_write_b16 v31, v26 offset:36720
	v_ashrrev_i32_e32 v26, 3, v36
	v_and_b32_e32 v27, -2, v26
	v_lshl_add_u32 v28, v27, 2, s34
	v_lshl_or_b32 v26, v26, 2, 4
	ds_read_b32 v28, v28
	v_add_u32_e32 v26, s34, v26
	ds_read_b32 v26, v26
	v_lshlrev_b32_e32 v29, 16, v18
	v_and_b32_e32 v18, 0xffff0000, v18
	v_sub_f32_e32 v33, v33, v32
	s_waitcnt lgkmcnt(1)
	v_sub_f32_e32 v18, v18, v28
	v_mul_f32_e32 v33, v30, v33
	s_waitcnt lgkmcnt(0)
	v_mul_f32_e32 v18, v26, v18
	v_fma_f32 v33, v14, v33, v22
	v_fma_f32 v18, v15, v18, v23
	v_cvt_pk_bf16_f32 v33, v33, s0
	v_lshlrev_b32_e32 v30, 16, v19
	v_add3_u32 v27, 0, v27, v0
	v_cvt_pk_bf16_f32 v18, v18, s0
	ds_write_b16 v31, v33 offset:34816
	ds_write_b16 v27, v18 offset:35088
	v_sub_f32_e32 v18, v30, v28
	v_mul_f32_e32 v18, v26, v18
	v_fma_f32 v18, v16, v18, v24
	v_and_b32_e32 v19, 0xffff0000, v19
	v_cvt_pk_bf16_f32 v18, v18, s0
	ds_write_b16 v27, v18 offset:35360
	v_sub_f32_e32 v18, v19, v28
	v_mul_f32_e32 v18, v26, v18
	v_fma_f32 v18, v17, v18, v25
	v_lshlrev_b32_e32 v31, 16, v20
	v_cvt_pk_bf16_f32 v18, v18, s0
	ds_write_b16 v27, v18 offset:35632
	v_sub_f32_e32 v18, v31, v28
	v_mul_f32_e32 v18, v26, v18
	v_fma_f32 v18, v6, v18, v10
	v_and_b32_e32 v20, 0xffff0000, v20
	v_cvt_pk_bf16_f32 v18, v18, s0
	ds_write_b16 v27, v18 offset:35904
	v_sub_f32_e32 v18, v20, v28
	v_mul_f32_e32 v18, v26, v18
	v_fma_f32 v18, v7, v18, v11
	v_lshlrev_b32_e32 v32, 16, v21
	v_cvt_pk_bf16_f32 v18, v18, s0
	ds_write_b16 v27, v18 offset:36176
	v_sub_f32_e32 v18, v32, v28
	v_mul_f32_e32 v18, v26, v18
	v_fma_f32 v18, v8, v18, v12
	v_and_b32_e32 v21, 0xffff0000, v21
	v_cvt_pk_bf16_f32 v18, v18, s0
	ds_write_b16 v27, v18 offset:36448
	v_sub_f32_e32 v18, v21, v28
	v_mul_f32_e32 v18, v26, v18
	v_fma_f32 v18, v9, v18, v13
	v_ashrrev_i32_e32 v19, 3, v35
	v_cvt_pk_bf16_f32 v18, v18, s0
	v_and_b32_e32 v20, -2, v19
	ds_write_b16 v27, v18 offset:36720
	v_lshl_add_u32 v18, v20, 2, s34
	v_lshl_or_b32 v19, v19, 2, 4
	ds_read_b32 v18, v18
	v_add_u32_e32 v19, s34, v19
	ds_read_b32 v19, v19
	v_lshlrev_b32_e32 v21, 16, v2
	v_and_b32_e32 v2, 0xffff0000, v2
	v_sub_f32_e32 v29, v29, v28
	s_waitcnt lgkmcnt(1)
	v_sub_f32_e32 v2, v2, v18
	v_mul_f32_e32 v29, v26, v29
	s_waitcnt lgkmcnt(0)
	v_mul_f32_e32 v2, v19, v2
	v_fma_f32 v29, v14, v29, v22
	v_fma_f32 v2, v15, v2, v23
	v_cvt_pk_bf16_f32 v29, v29, s0
	v_lshlrev_b32_e32 v26, 16, v3
	v_add3_u32 v0, 0, v20, v0
	v_cvt_pk_bf16_f32 v2, v2, s0
	ds_write_b16 v27, v29 offset:34816
	ds_write_b16 v0, v2 offset:35088
	v_sub_f32_e32 v2, v26, v18
	v_mul_f32_e32 v2, v19, v2
	v_fma_f32 v2, v16, v2, v24
	v_and_b32_e32 v3, 0xffff0000, v3
	v_cvt_pk_bf16_f32 v2, v2, s0
	ds_write_b16 v0, v2 offset:35360
	v_sub_f32_e32 v2, v3, v18
	v_mul_f32_e32 v2, v19, v2
	v_fmac_f32_e32 v25, v17, v2
	v_lshlrev_b32_e32 v27, 16, v4
	v_cvt_pk_bf16_f32 v2, v25, s0
	ds_write_b16 v0, v2 offset:35632
	v_sub_f32_e32 v2, v27, v18
	v_mul_f32_e32 v2, v19, v2
	v_fma_f32 v2, v6, v2, v10
	v_and_b32_e32 v4, 0xffff0000, v4
	v_cvt_pk_bf16_f32 v2, v2, s0
	ds_write_b16 v0, v2 offset:35904
	v_sub_f32_e32 v2, v4, v18
	v_mul_f32_e32 v2, v19, v2
	v_fma_f32 v2, v7, v2, v11
	v_lshlrev_b32_e32 v28, 16, v5
	v_cvt_pk_bf16_f32 v2, v2, s0
	ds_write_b16 v0, v2 offset:36176
	v_sub_f32_e32 v2, v28, v18
	v_mul_f32_e32 v2, v19, v2
	v_fma_f32 v2, v8, v2, v12
	v_and_b32_e32 v5, 0xffff0000, v5
	v_cvt_pk_bf16_f32 v2, v2, s0
	v_sub_f32_e32 v21, v21, v18
	ds_write_b16 v0, v2 offset:36448
	v_sub_f32_e32 v2, v5, v18
	v_mul_f32_e32 v21, v19, v21
	v_mul_f32_e32 v2, v19, v2
	v_fma_f32 v14, v14, v21, v22
	v_fmac_f32_e32 v13, v9, v2
	v_cvt_pk_bf16_f32 v14, v14, s0
	v_cvt_pk_bf16_f32 v2, v13, s0
	ds_write_b16 v0, v14 offset:34816
	ds_write_b16 v0, v2 offset:36720
	v_and_b32_e32 v0, 31, v34
	v_readlane_b32 s34, v253, 18
	v_lshlrev_b32_e32 v3, 4, v46
	s_waitcnt lgkmcnt(0)
	v_or_b32_e32 v2, s34, v0
	v_readlane_b32 s34, v253, 30
	v_mul_u32_u24_e32 v2, 0x110, v2
	s_barrier
; #define LAS __attribute__((address_space(3)))
; __device__ __forceinline__ unsigned cvt_pk_bf16(float lo, float hi) { const f32x2 v = {lo, hi}; const bf16x2_t b = __builtin_convertvector(v, bf16x2_t); return __builtin_bit_cast(unsigned, b); }
; __device__ __forceinline__ float bf_lo(unsigned u) { return __uint_as_float(u << 16); }
; __device__ __forceinline__ float bf_hi(unsigned u) { return __uint_as_float(u & 0xffff0000u); }
; template <bool STORE> __device__ __forceinline__ void sgu_unit(LAS unsigned char* lds, const bf16_t* GEL, const float* STAT, bf16_t* GU, const float* sw, const float* sb, const float* lng, const float* lnb, int unit, const int wave_s) {
;     ...
;     f32x16 d0 = {}, d1 = {};
; #pragma unroll
;     for (int ks = 0; ks < 8; ++ks) {
;         const bf16x8 af = *(const LAS bf16x8*)(lds + SG_GL + (32 * cb + q) * 272 + (16 * ks + 8 * hi) * 2);
;         const bf16x8 b0 = *(const LAS bf16x8*)(lds + SG_WL + (64 * th + q) * 272 + (16 * ks + 8 * hi) * 2);
;         const bf16x8 b1 = *(const LAS bf16x8*)(lds + SG_WL + (64 * th + 32 + q) * 272 + (16 * ks + 8 * hi) * 2);
;         d0 = __builtin_amdgcn_mfma_f32_32x32x16_bf16(af, b0, d0, 0, 0, 0);
;         d1 = __builtin_amdgcn_mfma_f32_32x32x16_bf16(af, b1, d1, 0, 0, 0);
;     }
; #pragma unroll
;     for (int tb = 0; tb < 2; ++tb) { const int t = 64 * th + 32 * tb + q; const float bias = sb[g * 128 + t];
;         bf16_t* rowp = GU + (size_t)(tok0 + t) * DM + c0 + 32 * cb + 4 * hi;
; #pragma unroll
;         for (int i = 0; i < 4; ++i) { const u32x2 u = *(const u32x2*)(rowp + 8 * i);
;             const float m0 = (tb ? d1[4 * i] : d0[4 * i]) + bias, m1 = (tb ? d1[4 * i + 1] : d0[4 * i + 1]) + bias, m2 = (tb ? d1[4 * i + 2] : d0[4 * i + 2]) + bias, m3 = (tb ? d1[4 * i + 3] : d0[4 * i + 3]) + bias;
;             u32x2 w; w.x = cvt_pk_bf16(bf_lo(u.x) * m0, bf_hi(u.x) * m1); w.y = cvt_pk_bf16(bf_lo(u.y) * m2, bf_hi(u.y) * m3);
;             if (STORE) *(u32x2*)(rowp + 8 * i) = w; } }
	v_or_b32_e32 v47, s34, v0
	v_mul_lo_u32 v0, v47, s45
	v_add3_u32 v0, 0, v0, v3
	v_add3_u32 v48, 0, v2, v3
	ds_read_b128 v[2:5], v0 offset:8704
	ds_read_b128 v[6:9], v48 offset:34816
	ds_read_b128 v[34:37], v48 offset:34848
	ds_read_b128 v[10:13], v0
	ds_read_b128 v[38:41], v0 offset:32
	s_waitcnt lgkmcnt(1)
	v_mfma_f32_32x32x16_bf16 v[18:33], v[6:9], v[10:13], 0
	ds_read_b128 v[42:45], v0 offset:8736
	s_lshl_b32 s34, s44, 1
	s_add_u32 s34, s40, s34
	s_addc_u32 s35, s41, 0
	v_mfma_f32_32x32x16_bf16 v[2:17], v[6:9], v[2:5], 0
	s_waitcnt lgkmcnt(1)
	v_mfma_f32_32x32x16_bf16 v[18:33], v[34:37], v[38:41], v[18:33]
	s_waitcnt lgkmcnt(0)
	v_mfma_f32_32x32x16_bf16 v[2:17], v[34:37], v[42:45], v[2:17]
	ds_read_b128 v[34:37], v48 offset:34880
	ds_read_b128 v[38:41], v0 offset:64
	ds_read_b128 v[42:45], v0 offset:8768
	s_waitcnt lgkmcnt(1)
	v_mfma_f32_32x32x16_bf16 v[18:33], v[34:37], v[38:41], v[18:33]
	s_waitcnt lgkmcnt(0)
	v_mfma_f32_32x32x16_bf16 v[2:17], v[34:37], v[42:45], v[2:17]
	ds_read_b128 v[34:37], v48 offset:34912
	ds_read_b128 v[38:41], v0 offset:96
	ds_read_b128 v[42:45], v0 offset:8800
	s_waitcnt lgkmcnt(1)
	v_mfma_f32_32x32x16_bf16 v[18:33], v[34:37], v[38:41], v[18:33]
	s_waitcnt lgkmcnt(0)
	v_mfma_f32_32x32x16_bf16 v[2:17], v[34:37], v[42:45], v[2:17]
	ds_read_b128 v[34:37], v48 offset:34944
	ds_read_b128 v[38:41], v0 offset:128
	ds_read_b128 v[42:45], v0 offset:8832
	s_waitcnt lgkmcnt(1)
	v_mfma_f32_32x32x16_bf16 v[18:33], v[34:37], v[38:41], v[18:33]
	s_waitcnt lgkmcnt(0)
	v_mfma_f32_32x32x16_bf16 v[2:17], v[34:37], v[42:45], v[2:17]
	ds_read_b128 v[34:37], v48 offset:34976
	ds_read_b128 v[38:41], v0 offset:160
	ds_read_b128 v[42:45], v0 offset:8864
	s_waitcnt lgkmcnt(1)
	v_mfma_f32_32x32x16_bf16 v[18:33], v[34:37], v[38:41], v[18:33]
	s_waitcnt lgkmcnt(0)
	v_mfma_f32_32x32x16_bf16 v[2:17], v[34:37], v[42:45], v[2:17]
	ds_read_b128 v[34:37], v48 offset:35008
	ds_read_b128 v[38:41], v0 offset:192
	ds_read_b128 v[42:45], v0 offset:8896
	s_waitcnt lgkmcnt(1)
	v_mfma_f32_32x32x16_bf16 v[18:33], v[34:37], v[38:41], v[18:33]
	s_waitcnt lgkmcnt(0)
	v_mfma_f32_32x32x16_bf16 v[2:17], v[34:37], v[42:45], v[2:17]
	ds_read_b128 v[34:37], v48 offset:35040
	ds_read_b128 v[38:41], v0 offset:224
	ds_read_b128 v[42:45], v0 offset:8928
	v_lshlrev_b32_e32 v0, 3, v46
	s_waitcnt lgkmcnt(1)
	v_mfma_f32_32x32x16_bf16 v[18:33], v[34:37], v[38:41], v[18:33]
	v_add_u32_e32 v38, s43, v47
	v_ashrrev_i32_e32 v39, 31, v38
	v_lshlrev_b64 v[40:41], 11, v[38:39]
	s_waitcnt lgkmcnt(0)
	v_mfma_f32_32x32x16_bf16 v[2:17], v[34:37], v[42:45], v[2:17]
	v_lshl_add_u64 v[34:35], s[34:35], 0, v[0:1]
	v_add_u32_e32 v0, s44, v47
	v_lshl_add_u64 v[36:37], v[0:1], 2, s[12:13]
	v_lshl_add_u64 v[40:41], v[34:35], 0, v[40:41]
	v_add_u32_e32 v170, 32, v38
	v_ashrrev_i32_e32 v171, 31, v170
	v_lshlrev_b64 v[170:171], 11, v[170:171]
	v_lshl_add_u64 v[170:171], v[34:35], 0, v[170:171]
	global_load_dword v168, v[36:37], off
	global_load_dwordx2 v[150:151], v[40:41], off
	global_load_dwordx2 v[152:153], v[40:41], off offset:16
	global_load_dwordx2 v[154:155], v[40:41], off offset:32
	global_load_dwordx2 v[156:157], v[40:41], off offset:48
	global_load_dword v169, v[36:37], off offset:128
	global_load_dwordx2 v[158:159], v[170:171], off
	global_load_dwordx2 v[160:161], v[170:171], off offset:16
	global_load_dwordx2 v[162:163], v[170:171], off offset:32
	global_load_dwordx2 v[164:165], v[170:171], off offset:48
	s_waitcnt vmcnt(8)
	v_add_f32_e32 v18, v18, v168
	v_add_f32_e32 v19, v19, v168
	v_add_f32_e32 v20, v20, v168
	v_add_f32_e32 v21, v21, v168
	v_lshlrev_b32_e32 v172, 16, v150
	v_and_b32_e32 v173, 0xffff0000, v150
	v_mul_f32_e32 v18, v18, v172
	v_mul_f32_e32 v19, v19, v173
	v_lshlrev_b32_e32 v172, 16, v151
	v_and_b32_e32 v173, 0xffff0000, v151
	v_mul_f32_e32 v20, v20, v172
	v_mul_f32_e32 v21, v21, v173
	v_cvt_pk_bf16_f32 v18, v18, v19
	v_cvt_pk_bf16_f32 v19, v20, v21
	global_store_dwordx2 v[40:41], v[18:19], off
	s_waitcnt vmcnt(8)
; __device__ __forceinline__ unsigned cvt_pk_bf16(float lo, float hi) { const f32x2 v = {lo, hi}; const bf16x2_t b = __builtin_convertvector(v, bf16x2_t); return __builtin_bit_cast(unsigned, b); }
; __device__ __forceinline__ float bf_lo(unsigned u) { return __uint_as_float(u << 16); }
; __device__ __forceinline__ float bf_hi(unsigned u) { return __uint_as_float(u & 0xffff0000u); }
; template <bool STORE> __device__ __forceinline__ void sgu_unit(LAS unsigned char* lds, const bf16_t* GEL, const float* STAT, bf16_t* GU, const float* sw, const float* sb, const float* lng, const float* lnb, int unit, const int wave_s) {
;     ...
;     for (int tb = 0; tb < 2; ++tb) { const int t = 64 * th + 32 * tb + q; const float bias = sb[g * 128 + t];
;         bf16_t* rowp = GU + (size_t)(tok0 + t) * DM + c0 + 32 * cb + 4 * hi;
; #pragma unroll
;         for (int i = 0; i < 4; ++i) { const u32x2 u = *(const u32x2*)(rowp + 8 * i);
;             const float m0 = (tb ? d1[4 * i] : d0[4 * i]) + bias, m1 = (tb ? d1[4 * i + 1] : d0[4 * i + 1]) + bias, m2 = (tb ? d1[4 * i + 2] : d0[4 * i + 2]) + bias, m3 = (tb ? d1[4 * i + 3] : d0[4 * i + 3]) + bias;
;             u32x2 w; w.x = cvt_pk_bf16(bf_lo(u.x) * m0, bf_hi(u.x) * m1); w.y = cvt_pk_bf16(bf_lo(u.y) * m2, bf_hi(u.y) * m3);
;             if (STORE) *(u32x2*)(rowp + 8 * i) = w; } }
	v_add_f32_e32 v22, v22, v168
	v_add_f32_e32 v23, v23, v168
	v_add_f32_e32 v24, v24, v168
	v_add_f32_e32 v25, v25, v168
	v_lshlrev_b32_e32 v172, 16, v152
	v_and_b32_e32 v173, 0xffff0000, v152
	v_mul_f32_e32 v22, v22, v172
	v_mul_f32_e32 v23, v23, v173
	v_lshlrev_b32_e32 v172, 16, v153
	v_and_b32_e32 v173, 0xffff0000, v153
	v_mul_f32_e32 v24, v24, v172
	v_mul_f32_e32 v25, v25, v173
	v_cvt_pk_bf16_f32 v22, v22, v23
	v_cvt_pk_bf16_f32 v23, v24, v25
	global_store_dwordx2 v[40:41], v[22:23], off offset:16
	s_waitcnt vmcnt(8)
	v_add_f32_e32 v26, v26, v168
	v_add_f32_e32 v27, v27, v168
	v_add_f32_e32 v28, v28, v168
	v_add_f32_e32 v29, v29, v168
	v_lshlrev_b32_e32 v172, 16, v154
	v_and_b32_e32 v173, 0xffff0000, v154
	v_mul_f32_e32 v26, v26, v172
	v_mul_f32_e32 v27, v27, v173
	v_lshlrev_b32_e32 v172, 16, v155
	v_and_b32_e32 v173, 0xffff0000, v155
	v_mul_f32_e32 v28, v28, v172
	v_mul_f32_e32 v29, v29, v173
	v_cvt_pk_bf16_f32 v26, v26, v27
	v_cvt_pk_bf16_f32 v27, v28, v29
	global_store_dwordx2 v[40:41], v[26:27], off offset:32
	s_waitcnt vmcnt(8)
	v_add_f32_e32 v30, v30, v168
	v_add_f32_e32 v31, v31, v168
	v_add_f32_e32 v32, v32, v168
	v_add_f32_e32 v33, v33, v168
	v_lshlrev_b32_e32 v172, 16, v156
	v_and_b32_e32 v173, 0xffff0000, v156
	v_mul_f32_e32 v30, v30, v172
	v_mul_f32_e32 v31, v31, v173
	v_lshlrev_b32_e32 v172, 16, v157
	v_and_b32_e32 v173, 0xffff0000, v157
	v_mul_f32_e32 v32, v32, v172
	v_mul_f32_e32 v33, v33, v173
	v_cvt_pk_bf16_f32 v30, v30, v31
	v_cvt_pk_bf16_f32 v31, v32, v33
	global_store_dwordx2 v[40:41], v[30:31], off offset:48
	s_waitcnt vmcnt(7)
	v_add_f32_e32 v2, v2, v169
	v_add_f32_e32 v3, v3, v169
	v_add_f32_e32 v4, v4, v169
	v_add_f32_e32 v5, v5, v169
	v_lshlrev_b32_e32 v172, 16, v158
	v_and_b32_e32 v173, 0xffff0000, v158
	v_mul_f32_e32 v2, v2, v172
	v_mul_f32_e32 v3, v3, v173
	v_lshlrev_b32_e32 v172, 16, v159
	v_and_b32_e32 v173, 0xffff0000, v159
	v_mul_f32_e32 v4, v4, v172
	v_mul_f32_e32 v5, v5, v173
	v_cvt_pk_bf16_f32 v2, v2, v3
	v_cvt_pk_bf16_f32 v3, v4, v5
	global_store_dwordx2 v[170:171], v[2:3], off
	s_waitcnt vmcnt(7)
	v_add_f32_e32 v6, v6, v169
	v_add_f32_e32 v7, v7, v169
	v_add_f32_e32 v8, v8, v169
	v_add_f32_e32 v9, v9, v169
	v_lshlrev_b32_e32 v172, 16, v160
	v_and_b32_e32 v173, 0xffff0000, v160
	v_mul_f32_e32 v6, v6, v172
	v_mul_f32_e32 v7, v7, v173
	v_lshlrev_b32_e32 v172, 16, v161
	v_and_b32_e32 v173, 0xffff0000, v161
	v_mul_f32_e32 v8, v8, v172
	v_mul_f32_e32 v9, v9, v173
	v_cvt_pk_bf16_f32 v6, v6, v7
	v_cvt_pk_bf16_f32 v7, v8, v9
	global_store_dwordx2 v[170:171], v[6:7], off offset:16
	s_waitcnt vmcnt(7)
	v_add_f32_e32 v10, v10, v169
	v_add_f32_e32 v11, v11, v169
	v_add_f32_e32 v12, v12, v169
	v_add_f32_e32 v13, v13, v169
	v_lshlrev_b32_e32 v172, 16, v162
	v_and_b32_e32 v173, 0xffff0000, v162
	v_mul_f32_e32 v10, v10, v172
	v_mul_f32_e32 v11, v11, v173
	v_lshlrev_b32_e32 v172, 16, v163
	v_and_b32_e32 v173, 0xffff0000, v163
	v_mul_f32_e32 v12, v12, v172
	v_mul_f32_e32 v13, v13, v173
	v_cvt_pk_bf16_f32 v10, v10, v11
	v_cvt_pk_bf16_f32 v11, v12, v13
	global_store_dwordx2 v[170:171], v[10:11], off offset:32
	s_waitcnt vmcnt(7)
	v_add_f32_e32 v14, v14, v169
	v_add_f32_e32 v15, v15, v169
	v_add_f32_e32 v16, v16, v169
	v_add_f32_e32 v17, v17, v169
	v_lshlrev_b32_e32 v172, 16, v164
	v_and_b32_e32 v173, 0xffff0000, v164
	v_mul_f32_e32 v14, v14, v172
	v_mul_f32_e32 v15, v15, v173
	v_lshlrev_b32_e32 v172, 16, v165
	v_and_b32_e32 v173, 0xffff0000, v165
	v_mul_f32_e32 v16, v16, v172
	v_mul_f32_e32 v17, v17, v173
	v_cvt_pk_bf16_f32 v14, v14, v15
	v_cvt_pk_bf16_f32 v15, v16, v17
	global_store_dwordx2 v[170:171], v[14:15], off offset:48
	s_barrier
